# phase 11a rewritten by hand (one gelu/scale/store per token, SALU addressing); W2 store deferred so no store is younger than the prefetch loads
# speedup vs baseline: 1.0440x; 1.0083x over previous
; DI void phase11a(const Params& P, char* smem_all) {
;     ...
;   for (int t = wslot; t < NTOK; t += nw) {
;     const int E0 = nE0, E1 = nE1; const float G0 = nG0, G1 = nG1, sx = nsx;
;     uint4 xr[4];
; #pragma unroll
;     for (int c = 0; c < 4; ++c) xr[c] = nx[c];
;     bool pf = false;
;     const int tn = t + nw < NTOK ? t + nw : t;
;     if (j == 0) { E2[(long)t * 128 + (lane & 7) * 16 + (lane >> 3)] = E0; E2[(long)t * 128 + (lane & 7) * 16 + 8 + (lane >> 3)] = E1; }
.LBB0_1441:
	s_or_b64 exec, exec, s[0:1]
	s_add_u32 s24, s78, 0x1b200000
	s_addc_u32 s25, s79, 0
	s_and_b32 s0, s22, -8
	v_add_u32_e32 v212, s0, v172
	s_and_b32 s5, s22, 7
	s_mov_b32 s22, 0x8000
	s_and_b32 s4, s64, -8
	v_cmp_gt_i32_e64 s[2:3], s22, v212
	v_ashrrev_i32_e32 v213, 31, v212
	s_waitcnt lgkmcnt(0)
	s_barrier
	s_and_saveexec_b64 s[26:27], s[2:3]
	s_cbranch_execz .LBB0_1525
	s_add_u32 s28, s78, 0x2100000
	s_addc_u32 s29, s79, 0
	s_add_u32 s32, s78, 0x2000000
	s_addc_u32 s33, s79, 0
	s_add_u32 s30, s78, 0x1b000000
	s_addc_u32 s31, s79, 0
	s_add_u32 s34, s78, 0x1c200000
	s_addc_u32 s35, s79, 0
	s_mov_b32 s19, 0xfffc00
	s_mov_b32 s23, 0
	v_lshlrev_b32_e32 v0, 2, v208
	v_and_b32_e32 v2, 15, v208
	v_lshrrev_b32_e32 v3, 4, v208
	v_lshlrev_b32_e32 v1, 4, v2
	v_and_b32_e32 v4, 0x3c00, v209
	v_lshlrev_b32_e32 v5, 3, v208
	v_add_u32_e32 v5, 0x2000, v5
	v_lshl_add_u32 v157, v2, 2, v3
	v_add_u32_e32 v166, 64, v208
	v_and_b32_e32 v158, 7, v208
	v_lshlrev_b32_e32 v158, 6, v158
	v_lshrrev_b32_e32 v159, 3, v208
	v_lshl_or_b32 v158, v159, 2, v158
	v_add_u32_e32 v159, 32, v158
	v_cmp_eq_u32_e64 s[80:81], 0, v2
	v_cmp_eq_u32_e64 s[82:83], 1, v2
	v_cmp_eq_u32_e64 s[84:85], 2, v2
	v_cmp_eq_u32_e64 s[86:87], 3, v2
	v_cmp_eq_u32_e64 s[88:89], 4, v2
	v_cmp_eq_u32_e64 s[90:91], 5, v2
	v_cmp_gt_u32_e64 s[94:95], 6, v2
	v_readfirstlane_b32 s6, v212
	s_nop 3
	s_mov_b32 s7, s6
	s_lshl_b32 s0, s7, 9
	s_add_u32 s8, s38, s0
	s_addc_u32 s9, s39, 0
	global_load_dword v10, v0, s[8:9]
	global_load_dword v11, v0, s[8:9] offset:256
	s_add_u32 s8, s42, s0
	s_addc_u32 s9, s43, 0
	global_load_dword v12, v0, s[8:9]
	global_load_dword v13, v0, s[8:9] offset:256
	s_lshl_b32 s0, s7, 10
	s_add_u32 s8, s62, s0
	s_addc_u32 s9, s63, 0
	global_load_dwordx4 v[32:35], v1, s[8:9]
	global_load_dwordx4 v[36:39], v1, s[8:9] offset:256
	global_load_dwordx4 v[40:43], v1, s[8:9] offset:512
	global_load_dwordx4 v[44:47], v1, s[8:9] offset:768
	s_lshl_b32 s0, s7, 2
	s_add_u32 s8, s30, s0
	s_addc_u32 s9, s31, 0
	s_load_dword s15, s[8:9], 0x0
	s_waitcnt vmcnt(0)
.Lp11a_tok:
	s_waitcnt vmcnt(0) lgkmcnt(0)
	v_mov_b32_e32 v6, v10
	v_mov_b32_e32 v7, v11
	v_mov_b32_e32 v8, v12
	v_mov_b32_e32 v9, v13
	v_mov_b64_e32 v[16:17], v[32:33]
	v_mov_b64_e32 v[18:19], v[34:35]
	v_mov_b64_e32 v[20:21], v[36:37]
	v_mov_b64_e32 v[22:23], v[38:39]
	v_mov_b64_e32 v[24:25], v[40:41]
	v_mov_b64_e32 v[26:27], v[42:43]
	v_mov_b64_e32 v[28:29], v[44:45]
	v_mov_b64_e32 v[30:31], v[46:47]
	s_mov_b32 s14, s15
	s_add_i32 s7, s6, s4
	s_cmp_lt_i32 s7, s22
	s_cselect_b32 s7, s7, s6
	s_lshl_b32 s0, s6, 9
	s_add_u32 s36, s24, s0
	s_addc_u32 s37, s25, 0
	s_cmp_eq_u32 s23, 0
	s_cbranch_scc1 .Lp11a_nopend
	s_and_saveexec_b64 s[92:93], s[72:73]
	global_store_dword v192, v193, s[74:75]
	s_mov_b64 exec, s[92:93]
	s_mov_b32 s23, 0
.Lp11a_nopend:
	s_cmp_lg_u32 s5, 0
	s_cbranch_scc1 .Lp11a_noe2
	s_add_u32 s20, s34, s0
	s_addc_u32 s21, s35, 0
	global_store_dword v158, v6, s[20:21]
	global_store_dword v159, v7, s[20:21]

; DI float gelu_t(float x) { float u = 0.7978845608028654f * (x + 0.044715f * x * x * x); float e = __expf(2.f * u); float t = 1.f - 2.f / (1.f + e); return 0.5f * x * (1.f + t); }
; DI void phase11a(const Params& P, char* smem_all) {
;     ...
;           d = dpp_row_sum_i(d);
;           const float dot = (float)d * (su[gi] * sx);
;           const float w = gl[gi] * gelu_t(dot) * sv[gi];
;           const int p = pl[gi];
;           if (l16 == 0 && p >= 0) W2[(long)t * 128 + (p & 7) * 16 + (p >> 3)] = w;
;         }
;       }
.Lp11a_dotted:
	s_nop 2
	v_add_u32_dpp v176, v176, v176 quad_perm:[1,0,3,2] row_mask:0xf bank_mask:0xf bound_ctrl:1
	v_add_u32_dpp v177, v177, v177 quad_perm:[1,0,3,2] row_mask:0xf bank_mask:0xf bound_ctrl:1
	v_add_u32_dpp v178, v178, v178 quad_perm:[1,0,3,2] row_mask:0xf bank_mask:0xf bound_ctrl:1
	v_add_u32_dpp v179, v179, v179 quad_perm:[1,0,3,2] row_mask:0xf bank_mask:0xf bound_ctrl:1
	v_add_u32_dpp v180, v180, v180 quad_perm:[1,0,3,2] row_mask:0xf bank_mask:0xf bound_ctrl:1
	v_add_u32_dpp v181, v181, v181 quad_perm:[1,0,3,2] row_mask:0xf bank_mask:0xf bound_ctrl:1
	v_add_u32_dpp v176, v176, v176 quad_perm:[2,3,0,1] row_mask:0xf bank_mask:0xf bound_ctrl:1
	v_add_u32_dpp v177, v177, v177 quad_perm:[2,3,0,1] row_mask:0xf bank_mask:0xf bound_ctrl:1
	v_add_u32_dpp v178, v178, v178 quad_perm:[2,3,0,1] row_mask:0xf bank_mask:0xf bound_ctrl:1
	v_add_u32_dpp v179, v179, v179 quad_perm:[2,3,0,1] row_mask:0xf bank_mask:0xf bound_ctrl:1
	v_add_u32_dpp v180, v180, v180 quad_perm:[2,3,0,1] row_mask:0xf bank_mask:0xf bound_ctrl:1
	v_add_u32_dpp v181, v181, v181 quad_perm:[2,3,0,1] row_mask:0xf bank_mask:0xf bound_ctrl:1
	v_add_u32_dpp v176, v176, v176 row_half_mirror row_mask:0xf bank_mask:0xf bound_ctrl:1
	v_add_u32_dpp v177, v177, v177 row_half_mirror row_mask:0xf bank_mask:0xf bound_ctrl:1
	v_add_u32_dpp v178, v178, v178 row_half_mirror row_mask:0xf bank_mask:0xf bound_ctrl:1
	v_add_u32_dpp v179, v179, v179 row_half_mirror row_mask:0xf bank_mask:0xf bound_ctrl:1
	v_add_u32_dpp v180, v180, v180 row_half_mirror row_mask:0xf bank_mask:0xf bound_ctrl:1
	v_add_u32_dpp v181, v181, v181 row_half_mirror row_mask:0xf bank_mask:0xf bound_ctrl:1
	v_add_u32_dpp v176, v176, v176 row_mirror row_mask:0xf bank_mask:0xf bound_ctrl:1
	v_add_u32_dpp v177, v177, v177 row_mirror row_mask:0xf bank_mask:0xf bound_ctrl:1
	v_add_u32_dpp v178, v178, v178 row_mirror row_mask:0xf bank_mask:0xf bound_ctrl:1
	v_add_u32_dpp v179, v179, v179 row_mirror row_mask:0xf bank_mask:0xf bound_ctrl:1
	v_add_u32_dpp v180, v180, v180 row_mirror row_mask:0xf bank_mask:0xf bound_ctrl:1
	v_add_u32_dpp v181, v181, v181 row_mirror row_mask:0xf bank_mask:0xf bound_ctrl:1
	v_cndmask_b32_e64 v152, v176, v177, s[82:83]
	v_cndmask_b32_e64 v152, v152, v178, s[84:85]
	v_cndmask_b32_e64 v152, v152, v179, s[86:87]
	v_cndmask_b32_e64 v152, v152, v180, s[88:89]
	v_cndmask_b32_e64 v152, v152, v181, s[90:91]
	v_cvt_f32_i32_e32 v182, v152
	v_mul_f32_e32 v183, s14, v156
	v_mul_f32_e32 v182, v183, v182
	v_mul_f32_e32 v183, 0x3d372713, v182
	v_mul_f32_e32 v183, v182, v183
	v_mul_f32_e32 v184, 0.5, v182
	v_fmac_f32_e32 v182, v182, v183
	v_mul_f32_e32 v182, 0x3f4c422a, v182
	v_add_f32_e32 v182, v182, v182
	v_mul_f32_e32 v182, 0x3fb8aa3b, v182
	v_exp_f32_e32 v182, v182
	v_and_b32_e32 v190, 0x7f, v154
	v_add_f32_e32 v182, 1.0, v182
	v_div_scale_f32 v185, s[0:1], v182, v182, 2.0
	v_rcp_f32_e32 v186, v185
	v_div_scale_f32 v187, vcc, 2.0, v182, 2.0
	v_fma_f32 v188, -v185, v186, 1.0
	v_fmac_f32_e32 v186, v188, v186
	v_mul_f32_e32 v188, v187, v186
	v_fma_f32 v189, -v185, v188, v187
	v_fmac_f32_e32 v188, v189, v186
	v_fma_f32 v187, -v185, v188, v187
	v_div_fmas_f32 v187, v187, v186, v188
	v_div_fixup_f32 v182, v187, v182, 2.0
	v_lshlrev_b32_e32 v191, 6, v190
	v_and_b32_e32 v191, 0x1c0, v191
	v_lshrrev_b32_e32 v190, 1, v190
	v_and_b32_e32 v190, 0x3c, v190
	v_or_b32_e32 v191, v191, v190
	v_sub_f32_e32 v182, 1.0, v182
	v_add_f32_e32 v182, 1.0, v182
	v_mul_f32_e32 v182, v184, v182
	v_mul_f32_e32 v182, v155, v182
	v_mul_f32_e32 v182, v153, v182
	s_cmp_lg_u32 s12, 0
	s_cbranch_scc1 .Lp11a_store_now
	v_mov_b32_e32 v192, v191
	v_mov_b32_e32 v193, v182
	s_mov_b64 s[72:73], s[16:17]
	s_mov_b64 s[74:75], s[36:37]
	s_mov_b32 s23, 1
	s_branch .Lp11a_chunk_end
.Lp11a_store_now:
	s_and_saveexec_b64 s[92:93], s[16:17]
	global_store_dword v191, v182, s[36:37]
	s_mov_b64 exec, s[92:93]
.Lp11a_chunk_end:
	s_add_i32 s12, s12, 24
	s_cmp_lt_u32 s12, s11
	s_cbranch_scc1 .Lp11a_chunk

; DI float gelu_t(float x) { float u = 0.7978845608028654f * (x + 0.044715f * x * x * x); float e = __expf(2.f * u); float t = 1.f - 2.f / (1.f + e); return 0.5f * x * (1.f + t); }
; DI void phase11a(const Params& P, char* smem_all) {
;     ...
;           const float w = gl[gi] * gelu_t(dot) * sv[gi];
;           const int p = pl[gi];
;           if (l16 == 0 && p >= 0) W2[(long)t * 128 + (p & 7) * 16 + (p >> 3)] = w;
.Lp11a_done:
	s_cmp_eq_u32 s23, 0
	s_cbranch_scc1 .Lp11a_flushed
	s_and_saveexec_b64 s[92:93], s[72:73]
	global_store_dword v192, v193, s[74:75]
	s_mov_b64 exec, s[92:93]
